# B loop v3: row sums by 4x4x4 ones-MFMA on the bf16 weights, no per-tile row-max pass (overflow detected from the tile row sum, full redo path), one extra mid-tile workgroup barrier keeps SIMD partners
# speedup vs baseline: 1.0433x; 1.0086x over previous
; #define LAS __attribute__((address_space(3)))
; DI float fexp2(float x) { return __builtin_amdgcn_exp2f(x); }
; DI float max2f(float a, float b) { float r; asm("v_max_f32_e32 %0, %1, %2" : "=v"(r) : "v"(a), "v"(b)); return r; }
; DI float xhalf_max(float v) { auto rr = __builtin_amdgcn_permlane32_swap(__float_as_uint(v), __float_as_uint(v), false, false); return max2f(__uint_as_float(rr[0]), __uint_as_float(rr[1])); }
; DI void attn_diff_unit(int ub, int Ssh, float lam, float post, const float* subg, const bf16_t* PROJ, bf16_t* O, LAS unsigned char* lds, int wid, int lane) {
;     ...
;     float mA = 0.f, mB = 0.f, lA = 0.f, lB = 0.f; f32x16 a0 = zero16(), a1 = zero16(), b0 = zero16(), b1 = zero16();
;     u32x4 kA = *(const u32x4*)ksrc, vA = *(const u32x4*)vsrc;
;     *(LAS u32x4*)(lds + kdst) = kA; *(LAS u32x4*)(lds + vdst) = vA;
;     __syncthreads();
;     const int vlane = ((lane >> 4) & 1) * 32 + (lane & 3) * 8 + (4 * hi + ((lane & 15) >> 2)) * 64;
;     auto tile = [&](const int t, LAS unsigned char* cur) {
;         f32x16 pa0, pa1, pb0, pb1; u32x4 pwA[4], pwB[4];
;         qk64<2, 0>(pa0, pa1, cur, qr, r32, hi);
;         qk64<2, 2>(pb0, pb1, cur, qr, r32, hi);
;         const float mxA = xhalf_max(rowmax32(pa0, pa1)), mxB = xhalf_max(rowmax32(pb0, pb1));
;         if (t == 0 || __any(mxA > mA + 8.0f || mxB > mB + 8.0f)) {
;             const float nA = (t == 0) ? mxA : max2f(mA, mxA), nB = (t == 0) ? mxB : max2f(mB, mxB);
;             const float fA = fexp2(mA - nA), fB = fexp2(mB - nB); mA = nA; mB = nB; lA *= fA; lB *= fB;
.Lbt_entry:
	v_add3_u32 v168, v213, v212, v211
	v_add3_u32 v169, v215, v214, v211
	v_add3_u32 v200, v217, v216, v211
	v_add3_u32 v201, v219, v218, v211
	v_add3_u32 v224, v207, v208, v209
	v_add_u32_e32 v224, v224, v210
	v_or_b32_e32 v168, 0x4000, v168
	v_or_b32_e32 v169, 0x4000, v169
	v_or_b32_e32 v200, 0x4000, v200
	v_or_b32_e32 v201, 0x4000, v201
	v_or_b32_e32 v224, 0x4000, v224
	v_sub_f32_e32 v176, 0, v220
	v_mov_b32_e32 v177, v176
	v_mov_b32_e32 v178, v176
	v_mov_b32_e32 v179, v176
	v_mov_b32_e32 v180, v176
	v_mov_b32_e32 v181, v176
	v_mov_b32_e32 v182, v176
	v_mov_b32_e32 v183, v176
	v_mov_b32_e32 v184, v176
	v_mov_b32_e32 v185, v176
	v_mov_b32_e32 v186, v176
	v_mov_b32_e32 v187, v176
	v_mov_b32_e32 v188, v176
	v_mov_b32_e32 v189, v176
	v_mov_b32_e32 v190, v176
	v_mov_b32_e32 v191, v176
	v_sub_f32_e32 v0, 0, v221
	v_mov_b32_e32 v208, v0
	v_mov_b32_e32 v209, v0
	v_mov_b32_e32 v210, v0
	v_mov_b32_e32 v211, v0
	v_mov_b32_e32 v212, v0
	v_mov_b32_e32 v213, v0
	v_mov_b32_e32 v214, v0
	v_mov_b32_e32 v215, v0
	v_mov_b32_e32 v216, v0
	v_mov_b32_e32 v217, v0
	v_mov_b32_e32 v218, v0
	v_mov_b32_e32 v219, v0
	v_mov_b32_e32 v220, v0
	v_mov_b32_e32 v221, v0
	v_mov_b32_e32 v222, v0
	v_mov_b32_e32 v223, v0
	v_mul_f32_e32 v156, 0.5, v156
	v_mul_f32_e32 v157, 0.5, v157
	v_mov_b32_e32 v226, 0x3f803f80
	v_mov_b32_e32 v227, 0x3f803f80

; #define LAS __attribute__((address_space(3)))
; DI void attn_diff_unit(int ub, int Ssh, float lam, float post, const float* subg, const bf16_t* PROJ, bf16_t* O, LAS unsigned char* lds, int wid, int lane) {
;     ...
;         qk64<2, 0>(pa0, pa1, cur, qr, r32, hi);
;         qk64<2, 2>(pb0, pb1, cur, qr, r32, hi);
;         const float mxA = xhalf_max(rowmax32(pa0, pa1)), mxB = xhalf_max(rowmax32(pb0, pb1));
;         if (t == 0 || __any(mxA > mA + 8.0f || mxB > mB + 8.0f)) {
;             const float nA = (t == 0) ? mxA : max2f(mA, mxA), nB = (t == 0) ? mxB : max2f(mB, mxB);
;             const float fA = fexp2(mA - nA), fB = fexp2(mB - nB); mA = nA; mB = nB; lA *= fA; lB *= fB;
; #pragma unroll
;             for (int r = 0; r < 16; ++r) { a0[r] *= fA; a1[r] *= fA; b0[r] *= fB; b1[r] *= fB; }
;         }
;         float sA = 0.f, sB = 0.f;
; #pragma unroll
;         for (int r = 0; r < 16; ++r) { pa0[r] = fexp2(pa0[r] - mA); pa1[r] = fexp2(pa1[r] - mA); sA += pa0[r] + pa1[r]; }
;         pwA[0] = (u32x4){cvtpk(pa0[0], pa0[1]), cvtpk(pa0[2], pa0[3]), cvtpk(pa0[4], pa0[5]), cvtpk(pa0[6], pa0[7])};
;         pwA[1] = (u32x4){cvtpk(pa0[8], pa0[9]), cvtpk(pa0[10], pa0[11]), cvtpk(pa0[12], pa0[13]), cvtpk(pa0[14], pa0[15])};
;         pwA[2] = (u32x4){cvtpk(pa1[0], pa1[1]), cvtpk(pa1[2], pa1[3]), cvtpk(pa1[4], pa1[5]), cvtpk(pa1[6], pa1[7])};
;         pwA[3] = (u32x4){cvtpk(pa1[8], pa1[9]), cvtpk(pa1[10], pa1[11]), cvtpk(pa1[12], pa1[13]), cvtpk(pa1[14], pa1[15])};
;         LAS const unsigned char* vp = cur + 8192 + vlane;
; #pragma unroll
;         for (int ks = 0; ks < 4; ++ks) {
;             const s16x4 lo0 = vtr(vp + ks * 1024), hi0 = vtr(vp + ks * 1024 + 512), lo1 = vtr(vp + 4096 + ks * 1024), hi1 = vtr(vp + 4096 + ks * 1024 + 512);
;             const bf16x8 v0 = (bf16x8){lo0[0], lo0[1], lo0[2], lo0[3], hi0[0], hi0[1], hi0[2], hi0[3]};
;             const bf16x8 v1 = (bf16x8){lo1[0], lo1[1], lo1[2], lo1[3], hi1[0], hi1[1], hi1[2], hi1[3]};
;             const bf16x8 pa = __builtin_bit_cast(bf16x8, pwA[ks]);
;             a0 = __builtin_amdgcn_mfma_f32_32x32x16_bf16(v0, pa, a0, 0, 0, 0);
;             a1 = __builtin_amdgcn_mfma_f32_32x32x16_bf16(v1, pa, a1, 0, 0, 0);
; #pragma unroll
;             for (int r = 4 * ks; r < 4 * ks + 4; ++r) { pb0[r] = fexp2(pb0[r] - mB); pb1[r] = fexp2(pb1[r] - mB); sB += pb0[r] + pb1[r]; }
.Lbt_nold:
	ds_read_b128 v[82:85], v168
	ds_read_b128 v[86:89], v169
	ds_read_b128 v[98:101], v168 offset:512
	ds_read_b128 v[102:105], v169 offset:512
	ds_read_b128 v[114:117], v200
	ds_read_b128 v[118:121], v201
	ds_read_b128 v[160:163], v200 offset:512
	ds_read_b128 v[164:167], v201 offset:512
	s_waitcnt lgkmcnt(6)
	v_mfma_f32_32x32x16_bf16 v[66:81], v[82:85], v[130:133], v[176:191]
	v_mfma_f32_32x32x16_bf16 v[66:81], v[86:89], v[134:137], v[66:81]
	s_waitcnt lgkmcnt(4)
	v_mfma_f32_32x32x16_bf16 v[82:97], v[98:101], v[130:133], v[176:191]
	v_mfma_f32_32x32x16_bf16 v[82:97], v[102:105], v[134:137], v[82:97]
	s_waitcnt lgkmcnt(2)
	v_mfma_f32_32x32x16_bf16 v[98:113], v[114:117], v[138:141], v[208:223]
	v_mfma_f32_32x32x16_bf16 v[98:113], v[118:121], v[142:145], v[98:113]
	s_waitcnt lgkmcnt(0)
	v_mfma_f32_32x32x16_bf16 v[114:129], v[160:163], v[138:141], v[208:223]
	v_mfma_f32_32x32x16_bf16 v[114:129], v[164:167], v[142:145], v[114:129]
	v_xor_b32_e32 v168, 0x4000, v168
	v_xor_b32_e32 v169, 0x4000, v169
	v_xor_b32_e32 v200, 0x4000, v200
	v_xor_b32_e32 v201, 0x4000, v201
	s_nop 1
	v_exp_f32_e32 v66, v66
	v_exp_f32_e32 v67, v67
	v_exp_f32_e32 v68, v68
	v_exp_f32_e32 v69, v69
	v_exp_f32_e32 v70, v70
	v_exp_f32_e32 v71, v71
	v_cvt_pk_bf16_f32 v66, v66, v67
	v_exp_f32_e32 v72, v72
	v_exp_f32_e32 v73, v73
	v_cvt_pk_bf16_f32 v67, v68, v69
	v_exp_f32_e32 v74, v74
	v_exp_f32_e32 v75, v75
	v_mfma_f32_4x4x4_16b_bf16 v[196:199], v[226:227], v[66:67], 0
	v_cvt_pk_bf16_f32 v68, v70, v71
	v_exp_f32_e32 v76, v76
	v_exp_f32_e32 v77, v77
	v_cvt_pk_bf16_f32 v69, v72, v73
	v_exp_f32_e32 v78, v78
	v_exp_f32_e32 v79, v79
	v_mfma_f32_4x4x4_16b_bf16 v[196:199], v[226:227], v[68:69], v[196:199]
	v_cvt_pk_bf16_f32 v70, v74, v75
	v_exp_f32_e32 v80, v80
	v_exp_f32_e32 v81, v81
	v_cvt_pk_bf16_f32 v71, v76, v77
	v_cvt_pk_bf16_f32 v72, v78, v79
	v_cvt_pk_bf16_f32 v73, v80, v81
	v_mfma_f32_4x4x4_16b_bf16 v[196:199], v[226:227], v[70:71], v[196:199]
	v_exp_f32_e32 v82, v82
	v_exp_f32_e32 v83, v83
	v_mfma_f32_4x4x4_16b_bf16 v[196:199], v[226:227], v[72:73], v[196:199]
	v_exp_f32_e32 v84, v84
	v_exp_f32_e32 v85, v85
	v_exp_f32_e32 v86, v86
	v_exp_f32_e32 v87, v87
	v_cvt_pk_bf16_f32 v82, v82, v83
	v_exp_f32_e32 v88, v88
	v_exp_f32_e32 v89, v89
	v_cvt_pk_bf16_f32 v83, v84, v85
	v_exp_f32_e32 v90, v90
	v_exp_f32_e32 v91, v91
	v_mfma_f32_4x4x4_16b_bf16 v[196:199], v[226:227], v[82:83], v[196:199]
	v_cvt_pk_bf16_f32 v84, v86, v87
	v_exp_f32_e32 v92, v92
	v_exp_f32_e32 v93, v93
	v_cvt_pk_bf16_f32 v85, v88, v89
	v_exp_f32_e32 v94, v94
	v_exp_f32_e32 v95, v95
	v_mfma_f32_4x4x4_16b_bf16 v[196:199], v[226:227], v[84:85], v[196:199]
	v_cvt_pk_bf16_f32 v86, v90, v91
	v_exp_f32_e32 v96, v96
	v_exp_f32_e32 v97, v97
	v_cvt_pk_bf16_f32 v87, v92, v93
	v_cvt_pk_bf16_f32 v88, v94, v95
	v_cvt_pk_bf16_f32 v89, v96, v97
	v_mfma_f32_4x4x4_16b_bf16 v[196:199], v[226:227], v[86:87], v[196:199]
	ds_read_b64_tr_b16 v[74:75], v224 offset:8192
	ds_read_b64_tr_b16 v[76:77], v224 offset:8704
	v_mfma_f32_4x4x4_16b_bf16 v[196:199], v[226:227], v[88:89], v[196:199]
	ds_read_b64_tr_b16 v[78:79], v224 offset:12288
	ds_read_b64_tr_b16 v[80:81], v224 offset:12800
	ds_read_b64_tr_b16 v[90:91], v224 offset:9216
	ds_read_b64_tr_b16 v[92:93], v224 offset:9728
	ds_read_b64_tr_b16 v[94:95], v224 offset:13312
	ds_read_b64_tr_b16 v[96:97], v224 offset:13824
	v_cmp_ngt_f32_e32 vcc, 0x5d800000, v196
	s_cbranch_vccnz .Lbt_redo_a
.Lbt_ok_a:
	v_add_f32_e32 v156, v156, v196
	s_barrier
	v_exp_f32_e32 v98, v98
	v_exp_f32_e32 v99, v99
	v_exp_f32_e32 v100, v100
	v_exp_f32_e32 v101, v101
	v_exp_f32_e32 v102, v102
	v_exp_f32_e32 v103, v103
	v_cvt_pk_bf16_f32 v98, v98, v99
	v_exp_f32_e32 v104, v104
	v_exp_f32_e32 v105, v105
	v_cvt_pk_bf16_f32 v99, v100, v101
	v_exp_f32_e32 v106, v106
	v_exp_f32_e32 v107, v107
	v_mfma_f32_4x4x4_16b_bf16 v[192:195], v[226:227], v[98:99], 0
	v_cvt_pk_bf16_f32 v100, v102, v103
	s_waitcnt lgkmcnt(0)
	v_mfma_f32_32x32x16_bf16 v[34:49], v[74:77], v[66:69], v[34:49]
	v_exp_f32_e32 v108, v108
	v_exp_f32_e32 v109, v109
	v_cvt_pk_bf16_f32 v101, v104, v105
	v_exp_f32_e32 v110, v110
	v_mfma_f32_32x32x16_bf16 v[2:17], v[78:81], v[66:69], v[2:17]
	v_exp_f32_e32 v111, v111
	v_mfma_f32_4x4x4_16b_bf16 v[192:195], v[226:227], v[100:101], v[192:195]
	v_cvt_pk_bf16_f32 v102, v106, v107
	v_exp_f32_e32 v112, v112
	v_mfma_f32_32x32x16_bf16 v[34:49], v[90:93], v[70:73], v[34:49]
	v_exp_f32_e32 v113, v113
	v_cvt_pk_bf16_f32 v103, v108, v109
	v_cvt_pk_bf16_f32 v104, v110, v111
	v_cvt_pk_bf16_f32 v105, v112, v113
	v_mfma_f32_32x32x16_bf16 v[2:17], v[94:97], v[70:73], v[2:17]
	v_mfma_f32_4x4x4_16b_bf16 v[192:195], v[226:227], v[102:103], v[192:195]
	v_exp_f32_e32 v114, v114
	v_exp_f32_e32 v115, v115
	ds_read_b64_tr_b16 v[74:75], v224 offset:10240
	ds_read_b64_tr_b16 v[76:77], v224 offset:10752
	ds_read_b64_tr_b16 v[78:79], v224 offset:14336
	ds_read_b64_tr_b16 v[80:81], v224 offset:14848
	ds_read_b64_tr_b16 v[90:91], v224 offset:11264
	ds_read_b64_tr_b16 v[92:93], v224 offset:11776
	ds_read_b64_tr_b16 v[94:95], v224 offset:15360
	ds_read_b64_tr_b16 v[96:97], v224 offset:15872
	v_mfma_f32_4x4x4_16b_bf16 v[192:195], v[226:227], v[104:105], v[192:195]
	v_exp_f32_e32 v116, v116
	v_exp_f32_e32 v117, v117
	v_exp_f32_e32 v118, v118
	v_exp_f32_e32 v119, v119
	v_cvt_pk_bf16_f32 v114, v114, v115
	v_exp_f32_e32 v120, v120
	v_exp_f32_e32 v121, v121
	v_cvt_pk_bf16_f32 v115, v116, v117
	v_exp_f32_e32 v122, v122
	v_exp_f32_e32 v123, v123
	v_mfma_f32_4x4x4_16b_bf16 v[192:195], v[226:227], v[114:115], v[192:195]
	s_waitcnt lgkmcnt(0)
; #define LAS __attribute__((address_space(3)))
; DI float fexp2(float x) { return __builtin_amdgcn_exp2f(x); }
; DI float max2f(float a, float b) { float r; asm("v_max_f32_e32 %0, %1, %2" : "=v"(r) : "v"(a), "v"(b)); return r; }
; DI float xhalf_max(float v) { auto rr = __builtin_amdgcn_permlane32_swap(__float_as_uint(v), __float_as_uint(v), false, false); return max2f(__uint_as_float(rr[0]), __uint_as_float(rr[1])); }
; DI s16x4 vtr(LAS const unsigned char* p) { return __builtin_bit_cast(s16x4, __builtin_amdgcn_ds_read_tr16_b64_v4i16((LAS v4i16_t*)p)); }
; DI void attn_diff_unit(int ub, int Ssh, float lam, float post, const float* subg, const bf16_t* PROJ, bf16_t* O, LAS unsigned char* lds, int wid, int lane) {
;     ...
;         const float mxA = xhalf_max(rowmax32(pa0, pa1)), mxB = xhalf_max(rowmax32(pb0, pb1));
;         if (t == 0 || __any(mxA > mA + 8.0f || mxB > mB + 8.0f)) {
;             const float nA = (t == 0) ? mxA : max2f(mA, mxA), nB = (t == 0) ? mxB : max2f(mB, mxB);
;             const float fA = fexp2(mA - nA), fB = fexp2(mB - nB); mA = nA; mB = nB; lA *= fA; lB *= fB;
; #pragma unroll
;             for (int r = 0; r < 16; ++r) { a0[r] *= fA; a1[r] *= fA; b0[r] *= fB; b1[r] *= fB; }
;         }
;     ...
; #pragma unroll
;         for (int ks = 0; ks < 4; ++ks) {
;             const s16x4 lo0 = vtr(vp + ks * 1024), hi0 = vtr(vp + ks * 1024 + 512), lo1 = vtr(vp + 4096 + ks * 1024), hi1 = vtr(vp + 4096 + ks * 1024 + 512);
;             const bf16x8 v0 = (bf16x8){lo0[0], lo0[1], lo0[2], lo0[3], hi0[0], hi0[1], hi0[2], hi0[3]};
;             const bf16x8 v1 = (bf16x8){lo1[0], lo1[1], lo1[2], lo1[3], hi1[0], hi1[1], hi1[2], hi1[3]};
;             const bf16x8 pb = __builtin_bit_cast(bf16x8, pwB[ks]);
;             b0 = __builtin_amdgcn_mfma_f32_32x32x16_bf16(v0, pb, b0, 0, 0, 0);
;             b1 = __builtin_amdgcn_mfma_f32_32x32x16_bf16(v1, pb, b1, 0, 0, 0);
;         }
;     };
;     for (int t = 0; t < NT; ++t) {
;         LAS unsigned char* cur = lds + (t & 1) * 16384; LAS unsigned char* nxt = lds + ((t + 1) & 1) * 16384;
;         if (t + 1 < NT) { kA = *(const u32x4*)(ksrc + (size_t)(t + 1) * 64 * PQ); vA = *(const u32x4*)(vsrc + (size_t)(t + 1) * 64 * PQ); }
;         tile(t, cur);
;         if (t + 1 < NT) { *(LAS u32x4*)(nxt + kdst) = kA; *(LAS u32x4*)(nxt + vdst) = vA; }
;         __syncthreads();
;     }
	v_mfma_f32_32x32x16_bf16 v[34:49], v[74:77], v[82:85], v[34:49]
	v_cvt_pk_bf16_f32 v116, v118, v119
	v_exp_f32_e32 v124, v124
	v_exp_f32_e32 v125, v125
	v_cvt_pk_bf16_f32 v117, v120, v121
	v_mfma_f32_32x32x16_bf16 v[2:17], v[78:81], v[82:85], v[2:17]
	v_exp_f32_e32 v126, v126
	v_exp_f32_e32 v127, v127
	v_mfma_f32_4x4x4_16b_bf16 v[192:195], v[226:227], v[116:117], v[192:195]
	v_cvt_pk_bf16_f32 v118, v122, v123
	v_mfma_f32_32x32x16_bf16 v[34:49], v[90:93], v[86:89], v[34:49]
	v_exp_f32_e32 v128, v128
	v_exp_f32_e32 v129, v129
	v_cvt_pk_bf16_f32 v119, v124, v125
	v_cvt_pk_bf16_f32 v120, v126, v127
	v_mfma_f32_32x32x16_bf16 v[2:17], v[94:97], v[86:89], v[2:17]
	v_cvt_pk_bf16_f32 v121, v128, v129
	v_mfma_f32_4x4x4_16b_bf16 v[192:195], v[226:227], v[118:119], v[192:195]
	ds_read_b64_tr_b16 v[84:85], v224 offset:10752
	ds_read_b64_tr_b16 v[66:67], v224 offset:8192
	ds_read_b64_tr_b16 v[68:69], v224 offset:8704
	ds_read_b64_tr_b16 v[70:71], v224 offset:12288
	ds_read_b64_tr_b16 v[72:73], v224 offset:12800
	ds_read_b64_tr_b16 v[74:75], v224 offset:9216
	ds_read_b64_tr_b16 v[76:77], v224 offset:9728
	ds_read_b64_tr_b16 v[78:79], v224 offset:13312
	ds_read_b64_tr_b16 v[80:81], v224 offset:13824
	ds_read_b64_tr_b16 v[82:83], v224 offset:10240
	ds_read_b64_tr_b16 v[86:87], v224 offset:14336
	v_mfma_f32_4x4x4_16b_bf16 v[192:195], v[226:227], v[120:121], v[192:195]
	ds_read_b64_tr_b16 v[88:89], v224 offset:14848
	ds_read_b64_tr_b16 v[90:91], v224 offset:11264
	ds_read_b64_tr_b16 v[92:93], v224 offset:11776
	ds_read_b64_tr_b16 v[94:95], v224 offset:15360
	ds_read_b64_tr_b16 v[96:97], v224 offset:15872
	v_cmp_ngt_f32_e32 vcc, 0x5d800000, v192
	s_cbranch_vccnz .Lbt_redo_b
.Lbt_ok_b:
	v_add_f32_e32 v157, v157, v192
	s_waitcnt lgkmcnt(0)
	v_mfma_f32_32x32x16_bf16 v[50:65], v[66:69], v[98:101], v[50:65]
	v_mfma_f32_32x32x16_bf16 v[18:33], v[70:73], v[98:101], v[18:33]
	v_mfma_f32_32x32x16_bf16 v[50:65], v[74:77], v[102:105], v[50:65]
	v_mfma_f32_32x32x16_bf16 v[18:33], v[78:81], v[102:105], v[18:33]
	v_mfma_f32_32x32x16_bf16 v[50:65], v[82:85], v[114:117], v[50:65]
	v_mfma_f32_32x32x16_bf16 v[18:33], v[86:89], v[114:117], v[18:33]
	v_mfma_f32_32x32x16_bf16 v[50:65], v[90:93], v[118:121], v[50:65]
	v_mfma_f32_32x32x16_bf16 v[18:33], v[94:97], v[118:121], v[18:33]
	s_andn2_b64 vcc, exec, s[2:3]
	s_cbranch_vccnz .Lbt_nowr
	s_waitcnt vmcnt(1)
	ds_write_b128 v205, v[146:149]
	s_waitcnt vmcnt(0)
	ds_write_b128 v206, v[150:153] offset:8192
.Lbt_nowr:
	v_xor_b32_e32 v205, 0x4000, v205
	v_xor_b32_e32 v206, 0x4000, v206
	v_xor_b32_e32 v224, 0x4000, v224
	s_mov_b64 s[0:1], 0x62000
	v_lshl_add_u64 v[158:159], v[158:159], 0, s[0:1]
	s_cmp_lg_u32 s39, s10
	s_waitcnt lgkmcnt(0)
	s_barrier
	s_cbranch_scc1 .Lbt_loop
	v_mov_b32_e32 v196, v156
	v_mov_b32_e32 v192, v157
	s_nop 1
	v_permlane32_swap_b32_e32 v156, v196
	v_permlane32_swap_b32_e32 v157, v192
	v_add_f32_e32 v156, v156, v196
	v_add_f32_e32 v157, v157, v192
	s_branch .LBB0_514
.Lbt_redo_a:
	v_xor_b32_e32 v0, 0x4000, v168
	v_xor_b32_e32 v207, 0x4000, v169
	ds_read_b128 v[82:85], v0
	ds_read_b128 v[86:89], v207
	ds_read_b128 v[160:163], v0 offset:512
	ds_read_b128 v[164:167], v207 offset:512
	s_waitcnt lgkmcnt(0)
	v_mfma_f32_32x32x16_bf16 v[66:81], v[82:85], v[130:133], v[176:191]
	v_mfma_f32_32x32x16_bf16 v[66:81], v[86:89], v[134:137], v[66:81]
	v_mfma_f32_32x32x16_bf16 v[82:97], v[160:163], v[130:133], v[176:191]
	v_mfma_f32_32x32x16_bf16 v[82:97], v[164:167], v[134:137], v[82:97]
	s_nop 7
	s_nop 7
	v_max3_f32 v196, v66, v67, v68
	v_max3_f32 v197, v69, v70, v71
	v_max3_f32 v196, v196, v72, v73
	v_max3_f32 v197, v197, v74, v75
	v_max3_f32 v196, v196, v76, v77
	v_max3_f32 v197, v197, v78, v79
	v_max3_f32 v196, v196, v80, v81
	v_max3_f32 v197, v197, v82, v83
	v_max3_f32 v196, v196, v84, v85
	v_max3_f32 v197, v197, v86, v87
	v_max3_f32 v196, v196, v88, v89
	v_max3_f32 v197, v197, v90, v91
	v_max3_f32 v196, v196, v92, v93
	v_max3_f32 v197, v197, v94, v95
	v_max3_f32 v196, v196, v96, v97
	v_max_f32_e32 v196, v196, v197
	v_mov_b32_e32 v197, v196
	s_nop 1
	v_permlane32_swap_b32_e32 v196, v197
	v_max_f32_e32 v196, v196, v197
	v_max_f32_e32 v196, 0, v196
	v_exp_f32_e64 v197, -v196
	v_sub_f32_e32 v176, v176, v196
	v_sub_f32_e32 v177, v177, v196
	v_sub_f32_e32 v178, v178, v196
	v_sub_f32_e32 v179, v179, v196
	v_sub_f32_e32 v180, v180, v196
	v_sub_f32_e32 v181, v181, v196
	v_sub_f32_e32 v182, v182, v196
	v_sub_f32_e32 v183, v183, v196
	v_sub_f32_e32 v184, v184, v196
	v_sub_f32_e32 v185, v185, v196
	v_sub_f32_e32 v186, v186, v196
	v_sub_f32_e32 v187, v187, v196
	v_sub_f32_e32 v188, v188, v196
	v_sub_f32_e32 v189, v189, v196
	v_sub_f32_e32 v190, v190, v196
	v_sub_f32_e32 v191, v191, v196
	v_sub_f32_e32 v66, v66, v196
	v_sub_f32_e32 v67, v67, v196
	v_sub_f32_e32 v68, v68, v196
	v_sub_f32_e32 v69, v69, v196
	v_sub_f32_e32 v70, v70, v196
	v_sub_f32_e32 v71, v71, v196
	v_sub_f32_e32 v72, v72, v196
	v_sub_f32_e32 v73, v73, v196
	v_sub_f32_e32 v74, v74, v196
	v_sub_f32_e32 v75, v75, v196
	v_sub_f32_e32 v76, v76, v196
	v_sub_f32_e32 v77, v77, v196
	v_sub_f32_e32 v78, v78, v196
	v_sub_f32_e32 v79, v79, v196
	v_sub_f32_e32 v80, v80, v196
	v_sub_f32_e32 v81, v81, v196
	v_sub_f32_e32 v82, v82, v196
	v_sub_f32_e32 v83, v83, v196
	v_sub_f32_e32 v84, v84, v196
	v_sub_f32_e32 v85, v85, v196
	v_sub_f32_e32 v86, v86, v196
	v_sub_f32_e32 v87, v87, v196
	v_sub_f32_e32 v88, v88, v196
	v_sub_f32_e32 v89, v89, v196
	v_sub_f32_e32 v90, v90, v196
	v_sub_f32_e32 v91, v91, v196
	v_sub_f32_e32 v92, v92, v196
	v_sub_f32_e32 v93, v93, v196
	v_sub_f32_e32 v94, v94, v196
	v_sub_f32_e32 v95, v95, v196
	v_sub_f32_e32 v96, v96, v196
	v_sub_f32_e32 v97, v97, v196
; DI unsigned cvtpk(float lo, float hi) { f32x2 v = {lo, hi}; bf16x2_t b = __builtin_convertvector(v, bf16x2_t); return __builtin_bit_cast(unsigned, b); }
; DI float fexp2(float x) { return __builtin_amdgcn_exp2f(x); }
; DI float max2f(float a, float b) { float r; asm("v_max_f32_e32 %0, %1, %2" : "=v"(r) : "v"(a), "v"(b)); return r; }
; DI void attn_diff_unit(int ub, int Ssh, float lam, float post, const float* subg, const bf16_t* PROJ, bf16_t* O, LAS unsigned char* lds, int wid, int lane) {
;     ...
;         if (t == 0 || __any(mxA > mA + 8.0f || mxB > mB + 8.0f)) {
;             const float nA = (t == 0) ? mxA : max2f(mA, mxA), nB = (t == 0) ? mxB : max2f(mB, mxB);
;             const float fA = fexp2(mA - nA), fB = fexp2(mB - nB); mA = nA; mB = nB; lA *= fA; lB *= fB;
; #pragma unroll
;             for (int r = 0; r < 16; ++r) { a0[r] *= fA; a1[r] *= fA; b0[r] *= fB; b1[r] *= fB; }
;         }
;         float sA = 0.f, sB = 0.f;
; #pragma unroll
;         for (int r = 0; r < 16; ++r) { pa0[r] = fexp2(pa0[r] - mA); pa1[r] = fexp2(pa1[r] - mA); sA += pa0[r] + pa1[r]; }
;         pwA[0] = (u32x4){cvtpk(pa0[0], pa0[1]), cvtpk(pa0[2], pa0[3]), cvtpk(pa0[4], pa0[5]), cvtpk(pa0[6], pa0[7])};
;         pwA[1] = (u32x4){cvtpk(pa0[8], pa0[9]), cvtpk(pa0[10], pa0[11]), cvtpk(pa0[12], pa0[13]), cvtpk(pa0[14], pa0[15])};
;         pwA[2] = (u32x4){cvtpk(pa1[0], pa1[1]), cvtpk(pa1[2], pa1[3]), cvtpk(pa1[4], pa1[5]), cvtpk(pa1[6], pa1[7])};
;         pwA[3] = (u32x4){cvtpk(pa1[8], pa1[9]), cvtpk(pa1[10], pa1[11]), cvtpk(pa1[12], pa1[13]), cvtpk(pa1[14], pa1[15])};
	v_mul_f32_e32 v156, v156, v197
	v_mul_f32_e32 v34, v34, v197
	v_mul_f32_e32 v35, v35, v197
	v_mul_f32_e32 v36, v36, v197
	v_mul_f32_e32 v37, v37, v197
	v_mul_f32_e32 v38, v38, v197
	v_mul_f32_e32 v39, v39, v197
	v_mul_f32_e32 v40, v40, v197
	v_mul_f32_e32 v41, v41, v197
	v_mul_f32_e32 v42, v42, v197
	v_mul_f32_e32 v43, v43, v197
	v_mul_f32_e32 v44, v44, v197
	v_mul_f32_e32 v45, v45, v197
	v_mul_f32_e32 v46, v46, v197
	v_mul_f32_e32 v47, v47, v197
	v_mul_f32_e32 v48, v48, v197
	v_mul_f32_e32 v49, v49, v197
	v_mul_f32_e32 v2, v2, v197
	v_mul_f32_e32 v3, v3, v197
	v_mul_f32_e32 v4, v4, v197
	v_mul_f32_e32 v5, v5, v197
	v_mul_f32_e32 v6, v6, v197
	v_mul_f32_e32 v7, v7, v197
	v_mul_f32_e32 v8, v8, v197
	v_mul_f32_e32 v9, v9, v197
	v_mul_f32_e32 v10, v10, v197
	v_mul_f32_e32 v11, v11, v197
	v_mul_f32_e32 v12, v12, v197
	v_mul_f32_e32 v13, v13, v197
	v_mul_f32_e32 v14, v14, v197
	v_mul_f32_e32 v15, v15, v197
	v_mul_f32_e32 v16, v16, v197
	v_mul_f32_e32 v17, v17, v197
	s_nop 1
	v_exp_f32_e32 v66, v66
	v_exp_f32_e32 v67, v67
	v_exp_f32_e32 v68, v68
	v_exp_f32_e32 v69, v69
	v_exp_f32_e32 v70, v70
	v_exp_f32_e32 v71, v71
	v_cvt_pk_bf16_f32 v66, v66, v67
	v_exp_f32_e32 v72, v72
	v_exp_f32_e32 v73, v73
	v_cvt_pk_bf16_f32 v67, v68, v69
	v_exp_f32_e32 v74, v74
	v_exp_f32_e32 v75, v75
	v_mfma_f32_4x4x4_16b_bf16 v[196:199], v[226:227], v[66:67], 0
	v_cvt_pk_bf16_f32 v68, v70, v71
	v_exp_f32_e32 v76, v76
	v_exp_f32_e32 v77, v77
	v_cvt_pk_bf16_f32 v69, v72, v73
	v_exp_f32_e32 v78, v78
	v_exp_f32_e32 v79, v79
	v_mfma_f32_4x4x4_16b_bf16 v[196:199], v[226:227], v[68:69], v[196:199]
	v_cvt_pk_bf16_f32 v70, v74, v75
	v_exp_f32_e32 v80, v80
	v_exp_f32_e32 v81, v81
	v_cvt_pk_bf16_f32 v71, v76, v77
	v_cvt_pk_bf16_f32 v72, v78, v79
	v_cvt_pk_bf16_f32 v73, v80, v81
	v_mfma_f32_4x4x4_16b_bf16 v[196:199], v[226:227], v[70:71], v[196:199]
	v_exp_f32_e32 v82, v82
	v_exp_f32_e32 v83, v83
	v_mfma_f32_4x4x4_16b_bf16 v[196:199], v[226:227], v[72:73], v[196:199]
	v_exp_f32_e32 v84, v84
	v_exp_f32_e32 v85, v85
	v_exp_f32_e32 v86, v86
	v_exp_f32_e32 v87, v87
	v_cvt_pk_bf16_f32 v82, v82, v83
	v_exp_f32_e32 v88, v88
	v_exp_f32_e32 v89, v89
	v_cvt_pk_bf16_f32 v83, v84, v85
	v_exp_f32_e32 v90, v90
	v_exp_f32_e32 v91, v91
	v_mfma_f32_4x4x4_16b_bf16 v[196:199], v[226:227], v[82:83], v[196:199]
	v_cvt_pk_bf16_f32 v84, v86, v87
	v_exp_f32_e32 v92, v92
	v_exp_f32_e32 v93, v93
	v_cvt_pk_bf16_f32 v85, v88, v89
	v_exp_f32_e32 v94, v94
	v_exp_f32_e32 v95, v95
	v_mfma_f32_4x4x4_16b_bf16 v[196:199], v[226:227], v[84:85], v[196:199]
	v_cvt_pk_bf16_f32 v86, v90, v91
	v_exp_f32_e32 v96, v96
	v_exp_f32_e32 v97, v97
	v_cvt_pk_bf16_f32 v87, v92, v93
	v_cvt_pk_bf16_f32 v88, v94, v95
	v_cvt_pk_bf16_f32 v89, v96, v97
	v_mfma_f32_4x4x4_16b_bf16 v[196:199], v[226:227], v[86:87], v[196:199]
	ds_read_b64_tr_b16 v[74:75], v224 offset:8192
	ds_read_b64_tr_b16 v[76:77], v224 offset:8704
	v_mfma_f32_4x4x4_16b_bf16 v[196:199], v[226:227], v[88:89], v[196:199]
	ds_read_b64_tr_b16 v[78:79], v224 offset:12288
	ds_read_b64_tr_b16 v[80:81], v224 offset:12800
	ds_read_b64_tr_b16 v[90:91], v224 offset:9216
	ds_read_b64_tr_b16 v[92:93], v224 offset:9728
	ds_read_b64_tr_b16 v[94:95], v224 offset:13312
	ds_read_b64_tr_b16 v[96:97], v224 offset:13824
	s_nop 4
	s_branch .Lbt_ok_a
; #define LAS __attribute__((address_space(3)))
; DI void attn_diff_unit(int ub, int Ssh, float lam, float post, const float* subg, const bf16_t* PROJ, bf16_t* O, LAS unsigned char* lds, int wid, int lane) {
;     ...
;         qk64<2, 2>(pb0, pb1, cur, qr, r32, hi);
;         const float mxA = xhalf_max(rowmax32(pa0, pa1)), mxB = xhalf_max(rowmax32(pb0, pb1));
;         if (t == 0 || __any(mxA > mA + 8.0f || mxB > mB + 8.0f)) {
;             const float nA = (t == 0) ? mxA : max2f(mA, mxA), nB = (t == 0) ? mxB : max2f(mB, mxB);
;             const float fA = fexp2(mA - nA), fB = fexp2(mB - nB); mA = nA; mB = nB; lA *= fA; lB *= fB;
; #pragma unroll
;             for (int r = 0; r < 16; ++r) { a0[r] *= fA; a1[r] *= fA; b0[r] *= fB; b1[r] *= fB; }
;         }
;         float sA = 0.f, sB = 0.f;
; #pragma unroll
;         for (int r = 0; r < 16; ++r) { pa0[r] = fexp2(pa0[r] - mA); pa1[r] = fexp2(pa1[r] - mA); sA += pa0[r] + pa1[r]; }
;         pwA[0] = (u32x4){cvtpk(pa0[0], pa0[1]), cvtpk(pa0[2], pa0[3]), cvtpk(pa0[4], pa0[5]), cvtpk(pa0[6], pa0[7])};
;         pwA[1] = (u32x4){cvtpk(pa0[8], pa0[9]), cvtpk(pa0[10], pa0[11]), cvtpk(pa0[12], pa0[13]), cvtpk(pa0[14], pa0[15])};
;         pwA[2] = (u32x4){cvtpk(pa1[0], pa1[1]), cvtpk(pa1[2], pa1[3]), cvtpk(pa1[4], pa1[5]), cvtpk(pa1[6], pa1[7])};
;         pwA[3] = (u32x4){cvtpk(pa1[8], pa1[9]), cvtpk(pa1[10], pa1[11]), cvtpk(pa1[12], pa1[13]), cvtpk(pa1[14], pa1[15])};
;         LAS const unsigned char* vp = cur + 8192 + vlane;
; #pragma unroll
;         for (int ks = 0; ks < 4; ++ks) {
;             const s16x4 lo0 = vtr(vp + ks * 1024), hi0 = vtr(vp + ks * 1024 + 512), lo1 = vtr(vp + 4096 + ks * 1024), hi1 = vtr(vp + 4096 + ks * 1024 + 512);
;             const bf16x8 v0 = (bf16x8){lo0[0], lo0[1], lo0[2], lo0[3], hi0[0], hi0[1], hi0[2], hi0[3]};
;             const bf16x8 v1 = (bf16x8){lo1[0], lo1[1], lo1[2], lo1[3], hi1[0], hi1[1], hi1[2], hi1[3]};
;             const bf16x8 pa = __builtin_bit_cast(bf16x8, pwA[ks]);
;             a0 = __builtin_amdgcn_mfma_f32_32x32x16_bf16(v0, pa, a0, 0, 0, 0);
;             a1 = __builtin_amdgcn_mfma_f32_32x32x16_bf16(v1, pa, a1, 0, 0, 0);
; #pragma unroll
;             for (int r = 4 * ks; r < 4 * ks + 4; ++r) { pb0[r] = fexp2(pb0[r] - mB); pb1[r] = fexp2(pb1[r] - mB); sB += pb0[r] + pb1[r]; }
;         }
;         lA += xhalf_sum(sA); lB += xhalf_sum(sB);
.Lbt_redo_b:
	v_xor_b32_e32 v0, 0x4000, v200
	v_xor_b32_e32 v207, 0x4000, v201
	ds_read_b128 v[114:117], v0
	ds_read_b128 v[118:121], v207
	ds_read_b128 v[160:163], v0 offset:512
	ds_read_b128 v[164:167], v207 offset:512
	s_waitcnt lgkmcnt(0)
	v_mfma_f32_32x32x16_bf16 v[98:113], v[114:117], v[138:141], v[208:223]
	v_mfma_f32_32x32x16_bf16 v[98:113], v[118:121], v[142:145], v[98:113]
	v_mfma_f32_32x32x16_bf16 v[114:129], v[160:163], v[138:141], v[208:223]
	v_mfma_f32_32x32x16_bf16 v[114:129], v[164:167], v[142:145], v[114:129]
	s_nop 7
	s_nop 7
	v_max3_f32 v192, v98, v99, v100
	v_max3_f32 v193, v101, v102, v103
	v_max3_f32 v192, v192, v104, v105
	v_max3_f32 v193, v193, v106, v107
	v_max3_f32 v192, v192, v108, v109
	v_max3_f32 v193, v193, v110, v111
	v_max3_f32 v192, v192, v112, v113
	v_max3_f32 v193, v193, v114, v115
	v_max3_f32 v192, v192, v116, v117
	v_max3_f32 v193, v193, v118, v119
	v_max3_f32 v192, v192, v120, v121
	v_max3_f32 v193, v193, v122, v123
	v_max3_f32 v192, v192, v124, v125
	v_max3_f32 v193, v193, v126, v127
	v_max3_f32 v192, v192, v128, v129
	v_max_f32_e32 v192, v192, v193
	v_mov_b32_e32 v193, v192
	s_nop 1
	v_permlane32_swap_b32_e32 v192, v193
	v_max_f32_e32 v192, v192, v193
	v_max_f32_e32 v192, 0, v192
	v_exp_f32_e64 v193, -v192
	v_sub_f32_e32 v208, v208, v192
	v_sub_f32_e32 v209, v209, v192
	v_sub_f32_e32 v210, v210, v192
	v_sub_f32_e32 v211, v211, v192
	v_sub_f32_e32 v212, v212, v192
	v_sub_f32_e32 v213, v213, v192
	v_sub_f32_e32 v214, v214, v192
	v_sub_f32_e32 v215, v215, v192
	v_sub_f32_e32 v216, v216, v192
	v_sub_f32_e32 v217, v217, v192
	v_sub_f32_e32 v218, v218, v192
	v_sub_f32_e32 v219, v219, v192
	v_sub_f32_e32 v220, v220, v192
	v_sub_f32_e32 v221, v221, v192
	v_sub_f32_e32 v222, v222, v192
	v_sub_f32_e32 v223, v223, v192
	v_sub_f32_e32 v98, v98, v192
	v_sub_f32_e32 v99, v99, v192
	v_sub_f32_e32 v100, v100, v192
	v_sub_f32_e32 v101, v101, v192
	v_sub_f32_e32 v102, v102, v192
	v_sub_f32_e32 v103, v103, v192
	v_sub_f32_e32 v104, v104, v192
	v_sub_f32_e32 v105, v105, v192
	v_sub_f32_e32 v106, v106, v192
	v_sub_f32_e32 v107, v107, v192
	v_sub_f32_e32 v108, v108, v192
	v_sub_f32_e32 v109, v109, v192
	v_sub_f32_e32 v110, v110, v192
	v_sub_f32_e32 v111, v111, v192
	v_sub_f32_e32 v112, v112, v192
	v_sub_f32_e32 v113, v113, v192
	v_sub_f32_e32 v114, v114, v192
	v_sub_f32_e32 v115, v115, v192
	v_sub_f32_e32 v116, v116, v192
	v_sub_f32_e32 v117, v117, v192
	v_sub_f32_e32 v118, v118, v192
	v_sub_f32_e32 v119, v119, v192
	v_sub_f32_e32 v120, v120, v192
	v_sub_f32_e32 v121, v121, v192
	v_sub_f32_e32 v122, v122, v192
	v_sub_f32_e32 v123, v123, v192
	v_sub_f32_e32 v124, v124, v192
	v_sub_f32_e32 v125, v125, v192
	v_sub_f32_e32 v126, v126, v192
	v_sub_f32_e32 v127, v127, v192
	v_sub_f32_e32 v128, v128, v192
	v_sub_f32_e32 v129, v129, v192
	v_mul_f32_e32 v157, v157, v193
	v_mul_f32_e32 v50, v50, v193
	v_mul_f32_e32 v51, v51, v193
	v_mul_f32_e32 v52, v52, v193
	v_mul_f32_e32 v53, v53, v193
	v_mul_f32_e32 v54, v54, v193
	v_mul_f32_e32 v55, v55, v193
	v_mul_f32_e32 v56, v56, v193
	v_mul_f32_e32 v57, v57, v193
	v_mul_f32_e32 v58, v58, v193
	v_mul_f32_e32 v59, v59, v193
	v_mul_f32_e32 v60, v60, v193
	v_mul_f32_e32 v61, v61, v193
	v_mul_f32_e32 v62, v62, v193
	v_mul_f32_e32 v63, v63, v193
	v_mul_f32_e32 v64, v64, v193
	v_mul_f32_e32 v65, v65, v193
	v_mul_f32_e32 v18, v18, v193
	v_mul_f32_e32 v19, v19, v193
	v_mul_f32_e32 v20, v20, v193
	v_mul_f32_e32 v21, v21, v193
	v_mul_f32_e32 v22, v22, v193
	v_mul_f32_e32 v23, v23, v193
	v_mul_f32_e32 v24, v24, v193
	v_mul_f32_e32 v25, v25, v193
	v_mul_f32_e32 v26, v26, v193
	v_mul_f32_e32 v27, v27, v193
	v_mul_f32_e32 v28, v28, v193
	v_mul_f32_e32 v29, v29, v193
	v_mul_f32_e32 v30, v30, v193
	v_mul_f32_e32 v31, v31, v193
	v_mul_f32_e32 v32, v32, v193
	v_mul_f32_e32 v33, v33, v193
	s_nop 1
	v_exp_f32_e32 v98, v98
	v_exp_f32_e32 v99, v99
	v_exp_f32_e32 v100, v100
	v_exp_f32_e32 v101, v101
	v_exp_f32_e32 v102, v102
	v_exp_f32_e32 v103, v103
	v_cvt_pk_bf16_f32 v98, v98, v99
	v_exp_f32_e32 v104, v104
	v_exp_f32_e32 v105, v105
	v_cvt_pk_bf16_f32 v99, v100, v101
	v_exp_f32_e32 v106, v106
	v_exp_f32_e32 v107, v107
	v_mfma_f32_4x4x4_16b_bf16 v[192:195], v[226:227], v[98:99], 0
	v_cvt_pk_bf16_f32 v100, v102, v103
	v_exp_f32_e32 v108, v108
	v_exp_f32_e32 v109, v109
	v_cvt_pk_bf16_f32 v101, v104, v105
	v_exp_f32_e32 v110, v110
	v_exp_f32_e32 v111, v111
	v_mfma_f32_4x4x4_16b_bf16 v[192:195], v[226:227], v[100:101], v[192:195]
	v_cvt_pk_bf16_f32 v102, v106, v107
	v_exp_f32_e32 v112, v112
	v_exp_f32_e32 v113, v113
	v_cvt_pk_bf16_f32 v103, v108, v109
	v_cvt_pk_bf16_f32 v104, v110, v111
	v_cvt_pk_bf16_f32 v105, v112, v113
	v_mfma_f32_4x4x4_16b_bf16 v[192:195], v[226:227], v[102:103], v[192:195]
	v_exp_f32_e32 v114, v114
	v_exp_f32_e32 v115, v115
	v_mfma_f32_4x4x4_16b_bf16 v[192:195], v[226:227], v[104:105], v[192:195]
	v_exp_f32_e32 v116, v116
	v_exp_f32_e32 v117, v117
	v_exp_f32_e32 v118, v118
	v_exp_f32_e32 v119, v119
	v_cvt_pk_bf16_f32 v114, v114, v115
	v_exp_f32_e32 v120, v120
	v_exp_f32_e32 v121, v121
	v_cvt_pk_bf16_f32 v115, v116, v117
	v_exp_f32_e32 v122, v122
	v_exp_f32_e32 v123, v123
	v_mfma_f32_4x4x4_16b_bf16 v[192:195], v[226:227], v[114:115], v[192:195]
	v_cvt_pk_bf16_f32 v116, v118, v119
	v_exp_f32_e32 v124, v124
	v_exp_f32_e32 v125, v125
	v_cvt_pk_bf16_f32 v117, v120, v121
	v_exp_f32_e32 v126, v126
	v_exp_f32_e32 v127, v127
	v_mfma_f32_4x4x4_16b_bf16 v[192:195], v[226:227], v[116:117], v[192:195]
	v_cvt_pk_bf16_f32 v118, v122, v123
	v_exp_f32_e32 v128, v128
	v_exp_f32_e32 v129, v129
	v_cvt_pk_bf16_f32 v119, v124, v125
	v_cvt_pk_bf16_f32 v120, v126, v127
	v_cvt_pk_bf16_f32 v121, v128, v129
	v_mfma_f32_4x4x4_16b_bf16 v[192:195], v[226:227], v[118:119], v[192:195]
	ds_read_b64_tr_b16 v[84:85], v224 offset:10752
	ds_read_b64_tr_b16 v[86:87], v224 offset:14336
	v_mfma_f32_4x4x4_16b_bf16 v[192:195], v[226:227], v[120:121], v[192:195]
	ds_read_b64_tr_b16 v[88:89], v224 offset:14848
	ds_read_b64_tr_b16 v[90:91], v224 offset:11264
	ds_read_b64_tr_b16 v[92:93], v224 offset:11776
	ds_read_b64_tr_b16 v[94:95], v224 offset:15360
	ds_read_b64_tr_b16 v[96:97], v224 offset:15872
	s_nop 4
	s_branch .Lbt_ok_b
